# P8 section reorder: half of each XCD's workgroups run gate GEMM+EpiPle first, other half run proj/gate sample rows first (desynchronised write-bound epilogue)
# speedup vs baseline: 1.0055x; 1.0017x over previous
; __global__ void __launch_bounds__(NWAVES * 64, 2) fwd_megakernel(Args args) {
;     ...
;     if (IN(8)) {
;         pg8::Gemm g{(const bf16*)(ws + WS_PE), (const bf16*)(ws + WS_WPP), MP, D, DPLE}; pg8::StaticOrder S; S.init(MP, D, F.G, (int)blockIdx.x);
;         pg8::EpiBf E{PRJ};
;         if (!spread) pg8::gemm_phase<pg8::EpiBf, pg8::StaticOrder, true, true>(F.lds, g, S, E);
;         ElemBf Es{PRJ};
;         gemm_sample_rows<ElemBf>(F, (const bf16*)(ws + WS_PE), (const bf16*)(ws + WS_WPP), DPLE, Es);
.LBB0_1197:
	s_mov_b32 s96, 0
	s_bfe_u32 s95, s2, 0x10003
	s_cmp_lt_i32 s28, 9
	s_cselect_b64 s[4:5], -1, 0
	s_and_b64 s[0:1], s[4:5], s[0:1]
	s_andn2_b64 vcc, exec, s[0:1]
	s_cbranch_vccnz .LBB0_1261
	s_add_u32 s6, s26, 0xcb90000
	s_addc_u32 s7, s27, 0
	s_add_u32 s8, s26, 0x2880000
	s_addc_u32 s9, s27, 0
	s_andn2_b64 vcc, exec, s[50:51]
	s_cbranch_vccnz .LBB0_1228
	v_mov_b32_e32 v12, v192
	s_movk_i32 s0, 0x100
	v_readfirstlane_b32 s20, v12
	s_cmpk_gt_i32 s2, 0xff
	s_cbranch_scc1 .LBB0_1228
	s_ashr_i32 s3, s2, 31
	s_lshr_b32 s1, s3, 29
	s_add_i32 s1, s2, s1
	s_and_b32 s4, s1, -8
	s_sub_i32 s10, s2, s4
	s_cmp_gt_i32 s10, -1
	s_cbranch_scc0 .LBB0_1202
	s_lshl_b32 s14, s10, 5
	s_cbranch_execz .LBB0_1203
	s_branch .LBB0_1204

; __global__ void __launch_bounds__(NWAVES * 64, 2) fwd_megakernel(Args args) {
;     ...
;         if (!spread) pg8::gemm_phase<pg8::EpiBf, pg8::StaticOrder, true, true>(F.lds, g, S, E);
;         ElemBf Es{PRJ};
;         gemm_sample_rows<ElemBf>(F, (const bf16*)(ws + WS_PE), (const bf16*)(ws + WS_WPP), DPLE, Es);
;         asm volatile("s_waitcnt vmcnt(0)" ::: "memory"); __syncthreads();
;     }
;     if (IN(8)) {
;         pg8::Gemm g{XG, (const bf16*)(ws + WS_WPG), MP, D, D}; pg8::StaticOrder S; S.init(MP, D, F.G, (int)blockIdx.x);
;         pg8::EpiPle E{XG, PRJ, F.out + OUT_Y, SS};
.LBB0_1228:
	s_cmp_lg_u32 s96, 0
	s_cbranch_scc1 .Lq8_b_go
	s_cmp_lg_u32 s95, 0
	s_cbranch_scc1 .Lq8_b_go
	s_mov_b64 s[74:75], s[26:27]
	s_mov_b32 s76, s49
	s_mov_b32 s77, s50
	s_mov_b64 exec, -1
	s_mov_b64 s[0:1], -1
	v_mov_b32_e32 v12, v192
	s_mov_b32 s96, 1
	s_branch .Lq8_d_go

; __global__ void __launch_bounds__(NWAVES * 64, 2) fwd_megakernel(Args args) {
;     ...
;         asm volatile("s_waitcnt vmcnt(0)" ::: "memory"); __syncthreads();
;     }
;     if (IN(8)) {
;         pg8::Gemm g{XG, (const bf16*)(ws + WS_WPG), MP, D, D}; pg8::StaticOrder S; S.init(MP, D, F.G, (int)blockIdx.x);
;         pg8::EpiPle E{XG, PRJ, F.out + OUT_Y, SS};
;         pg8::gemm_phase<pg8::EpiPle, pg8::StaticOrder, true, true>(F.lds, g, S, E);
.LBB0_1231:
	s_waitcnt vmcnt(0)
	v_mov_b32_e32 v12, v192
	s_waitcnt vmcnt(0) lgkmcnt(0)
	s_barrier
	s_cmp_eq_u32 s95, 0
	s_cbranch_scc1 .Lq8_d_g1
	s_cmp_lg_u32 s96, 0
	s_cbranch_scc1 .Lq8_d_go
	s_mov_b32 s78, s2
	s_add_u32 s6, s26, 0x2680000
	s_addc_u32 s7, s27, 0
	s_mov_b32 s96, 1
	s_branch .Lq8_e_go
.Lq8_d_g1:
	s_add_u32 s6, s74, 0x2680000
	s_addc_u32 s7, s75, 0
	s_mov_b32 s96, 3
	s_branch .Lq8_e_go
.Lq8_d_go:
	s_movk_i32 s4, 0x400
	v_readfirstlane_b32 s18, v12
	s_andn2_b64 vcc, exec, s[0:1]
	s_cbranch_vccnz .LBB0_1261
	s_ashr_i32 s3, s2, 31
	s_lshr_b32 s0, s3, 29
	s_add_i32 s6, s2, s0
	s_and_b32 s0, s6, -8
	s_sub_i32 s5, s2, s0
	s_cmp_gt_i32 s5, -1
	s_cbranch_scc0 .LBB0_1234
	s_lshl_b32 s12, s5, 5
	s_ashr_i32 s0, s6, 3
	s_cbranch_execz .LBB0_1235
	s_branch .LBB0_1236

; __global__ void __launch_bounds__(NWAVES * 64, 2) fwd_megakernel(Args args) {
;     ...
;     if (IN(8)) {
;         pg8::Gemm g{XG, (const bf16*)(ws + WS_WPG), MP, D, D}; pg8::StaticOrder S; S.init(MP, D, F.G, (int)blockIdx.x);
;         pg8::EpiPle E{XG, PRJ, F.out + OUT_Y, SS};
;         pg8::gemm_phase<pg8::EpiPle, pg8::StaticOrder, true, true>(F.lds, g, S, E);
;         ElemPle Es{XG, PRJ, F.out + OUT_Y, SS};
;         gemm_sample_rows<ElemPle>(F, XG, (const bf16*)(ws + WS_WPG), D, Es);
.LBB0_1259:
	s_cmp_eq_u32 s95, 0
	s_cbranch_scc0 .Lq8_e_g2
	s_cmp_eq_u32 s96, 1
	s_cbranch_scc0 .Lq8_e_go
	s_mov_b64 s[26:27], s[74:75]
	s_mov_b32 s49, s76
	s_mov_b32 s50, s77
	s_add_u32 s6, s74, 0xcb90000
	s_addc_u32 s7, s75, 0
	s_add_u32 s8, s74, 0x2880000
	s_addc_u32 s9, s75, 0
	s_mov_b32 s96, 2
	s_mov_b64 exec, -1
	s_waitcnt lgkmcnt(0)
	s_barrier
	s_branch .Lq8_b_go
.Lq8_e_g2:
	s_cmp_eq_u32 s96, 2
	s_cbranch_scc1 .Lq8_end

; __global__ void __launch_bounds__(NWAVES * 64, 2) fwd_megakernel(Args args) {
;     ...
;         asm volatile("s_waitcnt vmcnt(0)" ::: "memory"); __syncthreads();
;     }
;     if (IN(8)) {
;         pg8::Gemm g{XG, (const bf16*)(ws + WS_WPG), MP, D, D}; pg8::StaticOrder S; S.init(MP, D, F.G, (int)blockIdx.x);
;         pg8::EpiPle E{XG, PRJ, F.out + OUT_Y, SS};
;         pg8::gemm_phase<pg8::EpiPle, pg8::StaticOrder, true, true>(F.lds, g, S, E);
;         ElemPle Es{XG, PRJ, F.out + OUT_Y, SS};
;         gemm_sample_rows<ElemPle>(F, XG, (const bf16*)(ws + WS_WPG), D, Es);
.LBB0_1261:
	s_cmp_eq_u32 s95, 0
	s_cbranch_scc1 .Lq8_end
	s_cmp_eq_u32 s96, 1
	s_cbranch_scc0 .Lq8_end
	s_mov_b32 s2, s78
	s_mov_b64 exec, -1
	s_mov_b64 s[0:1], -1
	v_mov_b32_e32 v12, v192
	s_mov_b32 s96, 2
	s_waitcnt vmcnt(0) lgkmcnt(0)
	s_barrier
	s_branch .Lq8_d_go
